# SB: next unit's K/V tiles loaded into spare registers during the current unit's tile loops (loader latency hidden for units 2-4)
# speedup vs baseline: 1.0012x; 1.0012x over previous
; #define LAS __attribute__((address_space(3)))
; DI void sb_wg_unit(bf16_t* act, int b, int hh, int Qb, LAS unsigned char* lds, volatile LAS unsigned* ctl, int tid, int wid, int lane) {
;     const int r = lane & 31, h = lane >> 5;
;     const int Q = Qb * 256, q0 = Q + 32 * wid, qpos = q0 + r;
;     const size_t rowq = (size_t)b * SEQ + qpos;
; __global__ void __launch_bounds__(512, 2) hybrid_fwd(Params p) {
;     ...
;             volatile LAS unsigned* ctl = (volatile LAS unsigned*)(lds + LDS_CTL);
;             for (int u = wg; u < 1024; u += G) {
;                 const int Qb = u & 31, hh = (u >> 5) & 7, b = u >> 8;
;                 sb_wg_unit(act, b, hh, Qb, lds, ctl, tid, wid, lane);
.LBB0_331:
	v_readlane_b32 s6, v250, 7
	v_readlane_b32 s7, v250, 8
	s_andn2_b64 vcc, exec, s[6:7]
	s_cbranch_vccnz .LBB0_358
	s_lshl_b32 s8, s20, 10
	s_lshl_b32 s10, s20, 4
	s_and_b32 s9, s8, 0xfffff000
	s_and_b32 s10, s10, 48
	s_add_i32 s8, s8, 0
	v_lshlrev_b32_e32 v7, 4, v99
	v_and_b32_e32 v83, 31, v99
	v_lshlrev_b32_e32 v4, 1, v106
	v_lshlrev_b32_e32 v5, 3, v106
	s_add_i32 s10, s10, 0
	v_lshl_add_u32 v93, v106, 4, s8
	v_lshlrev_b32_e32 v6, 3, v99
	v_and_b32_e32 v7, 0xc0, v7
	s_movk_i32 s8, 0x100
	v_lshrrev_b32_e32 v2, 5, v106
	s_lshl_b32 s6, s20, 3
	v_lshlrev_b32_e32 v3, 4, v83
	v_and_b32_e32 v4, 32, v4
	v_and_b32_e32 v5, 24, v5
	s_add_i32 s9, s10, s9
	v_and_or_b32 v6, v6, s8, v7
	v_lshlrev_b32_e32 v0, 3, v2
	s_ashr_i32 s7, s6, 31
	v_lshlrev_b32_e32 v82, 2, v2
	s_addk_i32 s9, 0x2000
	v_or3_b32 v4, v6, v4, v5
	v_lshl_or_b32 v2, v2, 10, v3
	s_lshl_b32 s16, s20, 5
	v_cmp_eq_u32_e64 s[40:41], 0, v99
	v_cmp_gt_u32_e64 s[42:43], 32, v106
	v_cmp_ne_u32_e64 s[44:45], 0, v106
	v_lshl_add_u32 v92, v106, 6, s9
	v_or_b32_e32 v94, 0xffffff40, v106
	v_add_u32_e32 v95, 0, v4
	v_add_u32_e32 v96, 0, v2
	v_lshlrev_b32_e32 v0, 1, v0
	s_lshl_b64 s[46:47], s[6:7], 1
	s_mov_b32 s17, s2
	s_mov_b32 s100, 0
	v_and_b32_e32 v146, 7, v106
	v_lshl_add_u32 v146, s20, 3, v146
	v_lshrrev_b32_e32 v147, 3, v106
	v_add_u32_e32 v94, 0xffffff40, v146
	v_lshlrev_b32_e32 v93, 4, v146
	v_lshl_add_u32 v93, v147, 10, v93
	v_lshlrev_b32_e32 v92, 6, v146
	v_and_b32_e32 v148, 3, v147
	v_lshl_add_u32 v92, v148, 4, v92
	v_lshrrev_b32_e32 v148, 2, v147
	v_lshl_add_u32 v92, v148, 12, v92
	v_add_u32_e32 v92, 0x2000, v92
	v_lshlrev_b32_e32 v146, 4, v147
	v_mov_b32_e32 v147, 0
	s_branch .LBB0_334

; #define LAS __attribute__((address_space(3)))
; DI void sb_wg_unit(bf16_t* act, int b, int hh, int Qb, LAS unsigned char* lds, volatile LAS unsigned* ctl, int tid, int wid, int lane) {
;     const int r = lane & 31, h = lane >> 5;
;     const int Q = Qb * 256, q0 = Q + 32 * wid, qpos = q0 + r;
;     const size_t rowq = (size_t)b * SEQ + qpos;
;     bf16x8 qf[4]; load_q(qf, act + rowq * PITCH + C_QA + hh * 64, h);
;     f32x16 o0, o1;
; #pragma unroll
;     for (int i = 0; i < 16; ++i) { o0[i] = 0.f; o1[i] = 0.f; }
;     float C = 1.f;
;     const bf16_t* kgb = act + (size_t)b * SEQ * PITCH + C_KA + hh * 64;
;     int t = q0 >> 6;
;     bool done = false;
;     int t_top = (Q >> 6) + 3;
.LBB0_334:
	s_and_b32 s6, s17, 7
	s_lshl_b32 s6, s6, 5
	s_bfe_u32 s7, s17, 0x50003
	s_or_b32 s6, s6, s7
	s_andn2_b32 s7, s17, 0xff
	s_or_b32 s7, s6, s7
	s_lshl_b32 s38, s7, 2
	s_and_b32 s38, s38, 0x380
	s_and_b32 s10, s7, 31
	s_lshl_b32 s21, s10, 8
	s_ashr_i32 s6, s7, 8
	s_add_i32 s21, s21, s16
	v_or_b32_e32 v86, s21, v83
	s_ashr_i32 s7, s6, 31
	s_lshl_b64 s[8:9], s[6:7], 13
	v_ashrrev_i32_e32 v87, 31, v86
	v_lshl_add_u64 v[2:3], s[8:9], 0, v[86:87]
	v_mov_b64_e32 v[4:5], s[76:77]
	v_mad_u64_u32 v[4:5], s[8:9], v2, s31, v[4:5]
	v_mad_i32_i24 v5, v3, s31, v5
	v_lshl_add_u64 v[88:89], v[4:5], 0, s[38:39]
	v_lshl_add_u64 v[84:85], v[88:89], 0, v[0:1]
	global_load_dwordx4 v[66:69], v[84:85], off
	global_load_dwordx4 v[70:73], v[84:85], off offset:32
	global_load_dwordx4 v[74:77], v[84:85], off offset:64
	global_load_dwordx4 v[78:81], v[84:85], off offset:96
	s_mul_hi_i32 s7, s6, 0x6400000
	s_mul_i32 s6, s6, 0x6400000
	s_add_u32 s6, s76, s6
	s_addc_u32 s7, s77, s7
	s_add_u32 s6, s6, s38
	s_addc_u32 s7, s7, 0
	s_lshl_b32 s8, s10, 2
	s_ashr_i32 s24, s21, 6
	s_or_b32 s25, s8, 3
	v_mov_b32_e32 v18, v1
	v_mov_b32_e32 v19, v1
	v_mov_b32_e32 v20, v1
	v_mov_b32_e32 v21, v1
	v_mov_b32_e32 v22, v1
	v_mov_b32_e32 v23, v1
	v_mov_b32_e32 v24, v1
	v_mov_b32_e32 v25, v1
	v_mov_b32_e32 v26, v1
	v_mov_b32_e32 v27, v1
	v_mov_b32_e32 v28, v1
	v_mov_b32_e32 v29, v1
	v_mov_b32_e32 v30, v1
	v_mov_b32_e32 v31, v1
	v_mov_b32_e32 v32, v1
	v_mov_b32_e32 v33, v1
	s_waitcnt lgkmcnt(0)
	v_mov_b64_e32 v[2:3], v[18:19]
	v_mov_b32_e32 v91, 1.0
	s_mov_b64 s[8:9], 0
	s_mov_b32 s101, 0
	v_mov_b64_e32 v[4:5], v[20:21]
	v_mov_b64_e32 v[6:7], v[22:23]
	v_mov_b64_e32 v[8:9], v[24:25]
	v_mov_b64_e32 v[10:11], v[26:27]
	v_mov_b64_e32 v[12:13], v[28:29]
	v_mov_b64_e32 v[14:15], v[30:31]
	v_mov_b64_e32 v[16:17], v[32:33]
	s_branch .LBB0_336

; #define LAS __attribute__((address_space(3)))
; DI void coop_load_tiles(const bf16_t* kbase, int vdelta, int t_hi, int nt, LAS unsigned char* lds, int wid, int lane) {
; #pragma unroll 1
;     for (int s0 = 0; s0 < nt; s0 += 4) {
;         u32x4 kr[4], vr[4];
; #pragma unroll
;         for (int s = 0; s < 4; ++s) if (s0 + s < nt) { const bf16_t* src = kbase + (size_t)((t_hi - s0 - s) * 64 + lane) * PITCH + 8 * wid; kr[s] = *(const u32x4*)src; vr[s] = *(const u32x4*)(src + vdelta); }
; #pragma unroll
;         for (int s = 0; s < 4; ++s) if (s0 + s < nt) { *(LAS u32x4*)(lds + (s0 + s) * 16384 + wid * 1024 + lane * 16) = kr[s];
;             *(LAS u32x4*)(lds + (s0 + s) * 16384 + 8192 + (wid >> 2) * 4096 + lane * 64 + (wid & 3) * 16) = vr[s]; }
;     }
; }
; DI void sb_wg_unit(bf16_t* act, int b, int hh, int Qb, LAS unsigned char* lds, volatile LAS unsigned* ctl, int tid, int wid, int lane) {
;     ...
;         const int t_bot = (t_top - 7) > 0 ? (t_top - 7) : 0, nt = t_top - t_bot + 1;
;         __syncthreads();
;         if (tid == 0) ctl[7] = 0u;
;         coop_load_tiles(kgb, C_VA - C_KA, t_top, nt, lds, wid, lane);
;         __syncthreads();
.LBB0_336:
	s_barrier
	s_and_saveexec_b64 s[10:11], s[40:41]
	v_mov_b32_e32 v34, s5
	ds_write_b32 v34, v1
	s_or_b64 exec, exec, s[10:11]
	s_max_i32 s22, s25, 6
	s_add_i32 s23, s22, -6
	s_sub_i32 s26, s25, s23
	s_cmp_lt_i32 s26, 0
	s_cbranch_scc1 .LBB0_353
	v_lshl_add_u32 v87, s25, 6, v94
	v_add_u32_e32 v90, 0x10000, v93
	v_add_u32_e32 v97, 0x10000, v92
	s_cmp_lg_u32 s101, 0
	s_cbranch_scc1 .Lsb3_later
	s_mov_b32 s101, 1
	s_cmp_eq_u32 s100, 1
	s_cbranch_scc1 .Lsb3_have
	v_add_u32_e32 v136, 0xc0, v87
	v_lshl_add_u64 v[138:139], s[6:7], 0, v[146:147]
	v_mad_i64_i32 v[138:139], s[10:11], v136, s31, v[138:139]
	global_load_dwordx4 v[150:153], v[138:139], off offset:1024
	global_load_dwordx4 v[210:213], v[138:139], off offset:2048
	s_cmp_lt_i32 s26, 1
	s_cbranch_scc1 .Lsb3_ld1
	v_add_u32_e32 v136, 0x80, v87
	v_lshl_add_u64 v[138:139], s[6:7], 0, v[146:147]
	v_mad_i64_i32 v[138:139], s[10:11], v136, s31, v[138:139]
	global_load_dwordx4 v[154:157], v[138:139], off offset:1024
	global_load_dwordx4 v[214:217], v[138:139], off offset:2048
	s_cmp_lt_i32 s26, 2
	s_cbranch_scc1 .Lsb3_ld1
	v_add_u32_e32 v136, 64, v87
	v_lshl_add_u64 v[138:139], s[6:7], 0, v[146:147]
	v_mad_i64_i32 v[138:139], s[10:11], v136, s31, v[138:139]
	global_load_dwordx4 v[176:179], v[138:139], off offset:1024
	global_load_dwordx4 v[218:221], v[138:139], off offset:2048
	s_cmp_lt_i32 s26, 3
	s_cbranch_scc1 .Lsb3_ld1
	v_add_u32_e32 v136, 0, v87
	v_lshl_add_u64 v[138:139], s[6:7], 0, v[146:147]
	v_mad_i64_i32 v[138:139], s[10:11], v136, s31, v[138:139]
	global_load_dwordx4 v[180:183], v[138:139], off offset:1024
	global_load_dwordx4 v[222:225], v[138:139], off offset:2048
	s_cmp_lt_i32 s26, 4
	s_cbranch_scc1 .Lsb3_ld1
	v_add_u32_e32 v136, 0xffffffc0, v87
	v_lshl_add_u64 v[138:139], s[6:7], 0, v[146:147]
	v_mad_i64_i32 v[138:139], s[10:11], v136, s31, v[138:139]
	global_load_dwordx4 v[184:187], v[138:139], off offset:1024
	global_load_dwordx4 v[238:241], v[138:139], off offset:2048
	s_cmp_lt_i32 s26, 5
	s_cbranch_scc1 .Lsb3_ld1
	v_add_u32_e32 v136, 0xffffff80, v87
	v_lshl_add_u64 v[138:139], s[6:7], 0, v[146:147]
	v_mad_i64_i32 v[138:139], s[10:11], v136, s31, v[138:139]
	global_load_dwordx4 v[188:191], v[138:139], off offset:1024
	global_load_dwordx4 v[242:245], v[138:139], off offset:2048
	s_cmp_lt_i32 s26, 6
	s_cbranch_scc1 .Lsb3_ld1
	v_add_u32_e32 v136, 0xffffff40, v87
	v_lshl_add_u64 v[138:139], s[6:7], 0, v[146:147]
	v_mad_i64_i32 v[138:139], s[10:11], v136, s31, v[138:139]
	global_load_dwordx4 v[206:209], v[138:139], off offset:1024
	global_load_dwordx4 v[252:255], v[138:139], off offset:2048
.Lsb3_ld1:
.Lsb3_have:
	s_mov_b32 s100, 0
	s_waitcnt vmcnt(0)
	ds_write_b128 v93, v[150:153]
	ds_write_b128 v92, v[210:213]
	s_cmp_lt_i32 s26, 1
	s_cbranch_scc1 .Lsb3_wr1
	ds_write_b128 v93, v[154:157] offset:16384
	ds_write_b128 v92, v[214:217] offset:16384
	s_cmp_lt_i32 s26, 2
	s_cbranch_scc1 .Lsb3_wr1
	ds_write_b128 v93, v[176:179] offset:32768
	ds_write_b128 v92, v[218:221] offset:32768
	s_cmp_lt_i32 s26, 3
	s_cbranch_scc1 .Lsb3_wr1
	ds_write_b128 v93, v[180:183] offset:49152
	ds_write_b128 v92, v[222:225] offset:49152
	s_cmp_lt_i32 s26, 4
	s_cbranch_scc1 .Lsb3_wr1
	ds_write_b128 v90, v[184:187]
	ds_write_b128 v97, v[238:241]
	s_cmp_lt_i32 s26, 5
	s_cbranch_scc1 .Lsb3_wr1
	ds_write_b128 v90, v[188:191] offset:16384
	ds_write_b128 v97, v[242:245] offset:16384
	s_cmp_lt_i32 s26, 6
	s_cbranch_scc1 .Lsb3_wr1
	ds_write_b128 v90, v[206:209] offset:32768
	ds_write_b128 v97, v[252:255] offset:32768
.Lsb3_wr1:
	s_branch .Lsb3_done
.Lsb3_later:
	v_add_u32_e32 v136, 0xc0, v87
	v_lshl_add_u64 v[138:139], s[6:7], 0, v[146:147]
	v_mad_i64_i32 v[138:139], s[10:11], v136, s31, v[138:139]
	global_load_dwordx4 v[34:37], v[138:139], off offset:1024
	global_load_dwordx4 v[108:111], v[138:139], off offset:2048
	s_cmp_lt_i32 s26, 1
	s_cbranch_scc1 .Lsb3_ld2
	v_add_u32_e32 v136, 0x80, v87
	v_lshl_add_u64 v[138:139], s[6:7], 0, v[146:147]
	v_mad_i64_i32 v[138:139], s[10:11], v136, s31, v[138:139]
	global_load_dwordx4 v[38:41], v[138:139], off offset:1024
	global_load_dwordx4 v[112:115], v[138:139], off offset:2048
	s_cmp_lt_i32 s26, 2
	s_cbranch_scc1 .Lsb3_ld2
	v_add_u32_e32 v136, 64, v87
	v_lshl_add_u64 v[138:139], s[6:7], 0, v[146:147]
	v_mad_i64_i32 v[138:139], s[10:11], v136, s31, v[138:139]
	global_load_dwordx4 v[42:45], v[138:139], off offset:1024
	global_load_dwordx4 v[116:119], v[138:139], off offset:2048
	s_cmp_lt_i32 s26, 3
	s_cbranch_scc1 .Lsb3_ld2
	v_add_u32_e32 v136, 0, v87
	v_lshl_add_u64 v[138:139], s[6:7], 0, v[146:147]
	v_mad_i64_i32 v[138:139], s[10:11], v136, s31, v[138:139]
	global_load_dwordx4 v[46:49], v[138:139], off offset:1024
	global_load_dwordx4 v[120:123], v[138:139], off offset:2048
	s_cmp_lt_i32 s26, 4
	s_cbranch_scc1 .Lsb3_ld2
	v_add_u32_e32 v136, 0xffffffc0, v87
	v_lshl_add_u64 v[138:139], s[6:7], 0, v[146:147]
	v_mad_i64_i32 v[138:139], s[10:11], v136, s31, v[138:139]
	global_load_dwordx4 v[50:53], v[138:139], off offset:1024
	global_load_dwordx4 v[124:127], v[138:139], off offset:2048
	s_cmp_lt_i32 s26, 5
	s_cbranch_scc1 .Lsb3_ld2
	v_add_u32_e32 v136, 0xffffff80, v87
	v_lshl_add_u64 v[138:139], s[6:7], 0, v[146:147]
	v_mad_i64_i32 v[138:139], s[10:11], v136, s31, v[138:139]
	global_load_dwordx4 v[54:57], v[138:139], off offset:1024
	global_load_dwordx4 v[128:131], v[138:139], off offset:2048
	s_cmp_lt_i32 s26, 6
	s_cbranch_scc1 .Lsb3_ld2
	v_add_u32_e32 v136, 0xffffff40, v87
	v_lshl_add_u64 v[138:139], s[6:7], 0, v[146:147]
	v_mad_i64_i32 v[138:139], s[10:11], v136, s31, v[138:139]
	global_load_dwordx4 v[58:61], v[138:139], off offset:1024
	global_load_dwordx4 v[132:135], v[138:139], off offset:2048
; #define LAS __attribute__((address_space(3)))
; DI void coop_load_tiles(const bf16_t* kbase, int vdelta, int t_hi, int nt, LAS unsigned char* lds, int wid, int lane) {
; #pragma unroll 1
;     for (int s0 = 0; s0 < nt; s0 += 4) {
;         u32x4 kr[4], vr[4];
; #pragma unroll
;         for (int s = 0; s < 4; ++s) if (s0 + s < nt) { const bf16_t* src = kbase + (size_t)((t_hi - s0 - s) * 64 + lane) * PITCH + 8 * wid; kr[s] = *(const u32x4*)src; vr[s] = *(const u32x4*)(src + vdelta); }
; #pragma unroll
;         for (int s = 0; s < 4; ++s) if (s0 + s < nt) { *(LAS u32x4*)(lds + (s0 + s) * 16384 + wid * 1024 + lane * 16) = kr[s];
;             *(LAS u32x4*)(lds + (s0 + s) * 16384 + 8192 + (wid >> 2) * 4096 + lane * 64 + (wid & 3) * 16) = vr[s]; }
;     }
; }
; DI void sb_wg_unit(bf16_t* act, int b, int hh, int Qb, LAS unsigned char* lds, volatile LAS unsigned* ctl, int tid, int wid, int lane) {
;     ...
;         while (!done && t >= t_bot) {
;             const int kv0 = t * 64;
;             LAS const unsigned char* Ks = lds + (t_top - t) * 16384; LAS const unsigned char* Vs = Ks + 8192;
;             f32x16 p0, p1;
; #pragma unroll
;             for (int i = 0; i < 16; ++i) { p0[i] = 0.f; p1[i] = 0.f; }
;             qk_tile(p0, p1, Ks, qf, r, h);
;             const bool diag = (kv0 + 63 >= q0);
.Lsb3_ld2:
	s_waitcnt vmcnt(0)
	ds_write_b128 v93, v[34:37]
	ds_write_b128 v92, v[108:111]
	s_cmp_lt_i32 s26, 1
	s_cbranch_scc1 .Lsb3_wr2
	ds_write_b128 v93, v[38:41] offset:16384
	ds_write_b128 v92, v[112:115] offset:16384
	s_cmp_lt_i32 s26, 2
	s_cbranch_scc1 .Lsb3_wr2
	ds_write_b128 v93, v[42:45] offset:32768
	ds_write_b128 v92, v[116:119] offset:32768
	s_cmp_lt_i32 s26, 3
	s_cbranch_scc1 .Lsb3_wr2
	ds_write_b128 v93, v[46:49] offset:49152
	ds_write_b128 v92, v[120:123] offset:49152
	s_cmp_lt_i32 s26, 4
	s_cbranch_scc1 .Lsb3_wr2
	ds_write_b128 v90, v[50:53]
	ds_write_b128 v97, v[124:127]
	s_cmp_lt_i32 s26, 5
	s_cbranch_scc1 .Lsb3_wr2
	ds_write_b128 v90, v[54:57] offset:16384
	ds_write_b128 v97, v[128:131] offset:16384
	s_cmp_lt_i32 s26, 6
	s_cbranch_scc1 .Lsb3_wr2
	ds_write_b128 v90, v[58:61] offset:32768
	ds_write_b128 v97, v[132:135] offset:32768
.Lsb3_wr2:
.Lsb3_done:
.LBB0_353:
	s_cmp_lt_i32 s24, s23
	s_cselect_b64 s[10:11], -1, 0
	s_or_b64 s[10:11], s[8:9], s[10:11]
	s_and_b64 vcc, exec, s[10:11]
	s_waitcnt lgkmcnt(0)
	s_barrier
	v_lshlrev_b32_e32 v142, 1, v82
	v_mov_b32_e32 v143, v1
	v_lshl_add_u64 v[142:143], v[88:89], 0, v[142:143]
	global_load_dwordx2 v[160:161], v[142:143], off offset:3072
	global_load_dwordx2 v[162:163], v[142:143], off offset:3088
	global_load_dwordx2 v[164:165], v[142:143], off offset:3104
	global_load_dwordx2 v[166:167], v[142:143], off offset:3120
	global_load_dwordx2 v[168:169], v[142:143], off offset:3136
	global_load_dwordx2 v[170:171], v[142:143], off offset:3152
	global_load_dwordx2 v[172:173], v[142:143], off offset:3168
	global_load_dwordx2 v[174:175], v[142:143], off offset:3184
	s_cmp_lg_u32 s101, 1
	s_cbranch_scc1 .Lsb3_nopf
	s_mov_b32 s101, 2
	s_add_i32 s14, s17, s78
	s_cmpk_gt_i32 s14, 0x3ff
	s_cbranch_scc1 .Lsb3_nopf
	s_add_u32 s98, s6, 0x6400000
	s_addc_u32 s99, s7, 0
	s_mov_b32 s100, 1
	v_add_u32_e32 v136, 0xc0, v87
	v_lshl_add_u64 v[138:139], s[98:99], 0, v[146:147]
	v_mad_i64_i32 v[138:139], s[14:15], v136, s31, v[138:139]
	global_load_dwordx4 v[150:153], v[138:139], off offset:1024
	global_load_dwordx4 v[210:213], v[138:139], off offset:2048
	s_cmp_lt_i32 s26, 1
	s_cbranch_scc1 .Lsb3_ldp
	v_add_u32_e32 v136, 0x80, v87
	v_lshl_add_u64 v[138:139], s[98:99], 0, v[146:147]
	v_mad_i64_i32 v[138:139], s[14:15], v136, s31, v[138:139]
	global_load_dwordx4 v[154:157], v[138:139], off offset:1024
	global_load_dwordx4 v[214:217], v[138:139], off offset:2048
	s_cmp_lt_i32 s26, 2
	s_cbranch_scc1 .Lsb3_ldp
	v_add_u32_e32 v136, 64, v87
	v_lshl_add_u64 v[138:139], s[98:99], 0, v[146:147]
	v_mad_i64_i32 v[138:139], s[14:15], v136, s31, v[138:139]
	global_load_dwordx4 v[176:179], v[138:139], off offset:1024
	global_load_dwordx4 v[218:221], v[138:139], off offset:2048
	s_cmp_lt_i32 s26, 3
	s_cbranch_scc1 .Lsb3_ldp
	v_add_u32_e32 v136, 0, v87
	v_lshl_add_u64 v[138:139], s[98:99], 0, v[146:147]
	v_mad_i64_i32 v[138:139], s[14:15], v136, s31, v[138:139]
	global_load_dwordx4 v[180:183], v[138:139], off offset:1024
	global_load_dwordx4 v[222:225], v[138:139], off offset:2048
	s_cmp_lt_i32 s26, 4
	s_cbranch_scc1 .Lsb3_ldp
	v_add_u32_e32 v136, 0xffffffc0, v87
	v_lshl_add_u64 v[138:139], s[98:99], 0, v[146:147]
	v_mad_i64_i32 v[138:139], s[14:15], v136, s31, v[138:139]
	global_load_dwordx4 v[184:187], v[138:139], off offset:1024
	global_load_dwordx4 v[238:241], v[138:139], off offset:2048
	s_cmp_lt_i32 s26, 5
	s_cbranch_scc1 .Lsb3_ldp
	v_add_u32_e32 v136, 0xffffff80, v87
	v_lshl_add_u64 v[138:139], s[98:99], 0, v[146:147]
	v_mad_i64_i32 v[138:139], s[14:15], v136, s31, v[138:139]
	global_load_dwordx4 v[188:191], v[138:139], off offset:1024
	global_load_dwordx4 v[242:245], v[138:139], off offset:2048
	s_cmp_lt_i32 s26, 6
	s_cbranch_scc1 .Lsb3_ldp
	v_add_u32_e32 v136, 0xffffff40, v87
	v_lshl_add_u64 v[138:139], s[98:99], 0, v[146:147]
	v_mad_i64_i32 v[138:139], s[14:15], v136, s31, v[138:139]
	global_load_dwordx4 v[206:209], v[138:139], off offset:1024
	global_load_dwordx4 v[252:255], v[138:139], off offset:2048
.Lsb3_ldp:
.Lsb3_nopf:
	s_cbranch_vccnz .LBB0_356
	s_lshl_b32 s8, s24, 6
	s_or_b32 s12, s8, 63
	s_lshl_b32 s8, s24, 14
	s_lshl_b32 s13, s25, 14
	v_subrev_u32_e32 v87, s8, v95
	v_subrev_u32_e32 v97, s8, v96
.LBB0_355:
	v_add_u32_e32 v90, s13, v97
	ds_read_b128 v[34:37], v90
	ds_read_b128 v[38:41], v90 offset:512
	ds_read_b128 v[100:103], v90 offset:2048
	ds_read_b128 v[108:111], v90 offset:2560
	s_cmp_lt_i32 s12, s21
	s_cselect_b64 s[8:9], -1, 0
	s_waitcnt vmcnt(22) lgkmcnt(3)
	v_mfma_f32_32x32x16_bf16 v[50:65], v[34:37], v[66:69], 0
	s_mov_b32 s10, s24
	v_add_u32_e32 v97, 0x4000, v97
	s_waitcnt lgkmcnt(2)
	v_mfma_f32_32x32x16_bf16 v[34:49], v[38:41], v[66:69], 0
	s_waitcnt lgkmcnt(1)
	v_mfma_f32_32x32x16_bf16 v[50:65], v[100:103], v[70:73], v[50:65]
	s_waitcnt lgkmcnt(0)
	v_mfma_f32_32x32x16_bf16 v[34:49], v[108:111], v[70:73], v[34:49]
	ds_read_b128 v[100:103], v90 offset:4096
	ds_read_b128 v[108:111], v90 offset:4608
	s_waitcnt lgkmcnt(1)
	v_mfma_f32_32x32x16_bf16 v[50:65], v[100:103], v[74:77], v[50:65]
	s_waitcnt lgkmcnt(0)
	v_mfma_f32_32x32x16_bf16 v[34:49], v[108:111], v[74:77], v[34:49]
	ds_read_b128 v[100:103], v90 offset:6144
	ds_read_b128 v[108:111], v90 offset:6656
	v_add_u32_e32 v90, s12, v82
	v_subrev_u32_e32 v98, 63, v90
	v_cmp_lt_i32_e32 vcc, v98, v86
	s_or_b64 vcc, s[8:9], vcc
	s_waitcnt lgkmcnt(1)
	v_mfma_f32_32x32x16_bf16 v[50:65], v[100:103], v[78:81], v[50:65]
	v_subrev_u32_e32 v103, 30, v90
	s_waitcnt lgkmcnt(0)
; DI float fast_exp2(float x) { return __builtin_amdgcn_exp2f(x); }
; DI float fast_rcp(float x) { return __builtin_amdgcn_rcpf(x); }
; DI void sb_wg_unit(bf16_t* act, int b, int hh, int Qb, LAS unsigned char* lds, volatile LAS unsigned* ctl, int tid, int wid, int lane) {
;     ...
;             qk_tile(p0, p1, Ks, qf, r, h);
;             const bool diag = (kv0 + 63 >= q0);
;             f32x16 F0, F1;
; #pragma unroll
;             for (int i = 0; i < 16; ++i) {
;                 const int kl = (i & 3) + 8 * (i >> 2) + 4 * h;
;                 { const float e = fast_exp2(fminf(p0[i], 60.f)); const float f = fast_rcp(1.f + e);
;                   const bool valid = !diag || (kv0 + kl < qpos); F0[i] = valid ? f : 1.f; p0[i] = valid ? e * f : 0.f; }
;                 { const float e = fast_exp2(fminf(p1[i], 60.f)); const float f = fast_rcp(1.f + e);
;                   const bool valid = !diag || (kv0 + 32 + kl < qpos); F1[i] = valid ? f : 1.f; p1[i] = valid ? e * f : 0.f; }
;             }
	v_mfma_f32_32x32x16_bf16 v[34:49], v[108:111], v[78:81], v[34:49]
	s_nop 8
	v_min_f32_e32 v50, 0x42700000, v50
	v_exp_f32_e32 v100, v50
	s_nop 0
	v_add_f32_e32 v50, 1.0, v100
	v_min_f32_e32 v34, 0x42700000, v34
	v_rcp_f32_e32 v101, v50
	v_exp_f32_e32 v34, v34
	v_min_f32_e32 v35, 0x42700000, v35
	v_mul_f32_e32 v98, v100, v101
	v_add_f32_e32 v100, 1.0, v34
	v_rcp_f32_e32 v100, v100
	v_cndmask_b32_e32 v50, 1.0, v101, vcc
	v_subrev_u32_e32 v101, 31, v90
	v_cndmask_b32_e32 v98, 0, v98, vcc
	v_cmp_lt_i32_e32 vcc, v101, v86
	s_or_b64 vcc, s[8:9], vcc
	v_mul_f32_e32 v34, v34, v100
	v_cndmask_b32_e32 v101, 1.0, v100, vcc
	v_cndmask_b32_e32 v100, 0, v34, vcc
	v_min_f32_e32 v34, 0x42700000, v51
	v_exp_f32_e32 v51, v34
	v_exp_f32_e32 v35, v35
	v_add_f32_e32 v34, 1.0, v51
	v_rcp_f32_e32 v102, v34
	v_subrev_u32_e32 v34, 62, v90
	v_cmp_lt_i32_e32 vcc, v34, v86
	s_or_b64 vcc, s[8:9], vcc
	v_mul_f32_e32 v51, v51, v102
	v_cndmask_b32_e32 v34, 1.0, v102, vcc
	v_cndmask_b32_e32 v102, 0, v51, vcc
	v_add_f32_e32 v51, 1.0, v35
	v_rcp_f32_e32 v51, v51
	v_cmp_lt_i32_e32 vcc, v103, v86
	s_or_b64 vcc, s[8:9], vcc
	v_mul_f32_e32 v35, v35, v51
	v_cndmask_b32_e32 v104, 0, v35, vcc
	v_min_f32_e32 v35, 0x42700000, v52
	v_exp_f32_e32 v35, v35
	v_cndmask_b32_e32 v103, 1.0, v51, vcc
	v_subrev_u32_e32 v52, 61, v90
	v_cmp_lt_i32_e32 vcc, v52, v86
	v_add_f32_e32 v51, 1.0, v35
	v_rcp_f32_e32 v51, v51
	s_or_b64 vcc, s[8:9], vcc
	v_mul_f32_e32 v35, v35, v51
	v_cndmask_b32_e32 v105, 0, v35, vcc
	v_min_f32_e32 v35, 0x42700000, v36
	v_exp_f32_e32 v35, v35
	v_cndmask_b32_e32 v52, 1.0, v51, vcc
	v_subrev_u32_e32 v51, 29, v90
	v_cmp_lt_i32_e32 vcc, v51, v86
	v_add_f32_e32 v36, 1.0, v35
	v_rcp_f32_e32 v36, v36
	s_or_b64 vcc, s[8:9], vcc
	v_mul_f32_e32 v35, v35, v36
	v_cndmask_b32_e32 v108, 0, v35, vcc
	v_min_f32_e32 v35, 0x42700000, v53
	v_exp_f32_e32 v35, v35
	v_cndmask_b32_e32 v107, 1.0, v36, vcc
	v_add_f32_e32 v36, 1.0, v35
	v_rcp_f32_e32 v51, v36
	v_subrev_u32_e32 v36, 60, v90
	v_cmp_lt_i32_e32 vcc, v36, v86
	s_or_b64 vcc, s[8:9], vcc
	v_mul_f32_e32 v35, v35, v51
	v_cndmask_b32_e32 v109, 0, v35, vcc
	v_min_f32_e32 v35, 0x42700000, v37
	v_exp_f32_e32 v35, v35
	v_cndmask_b32_e32 v36, 1.0, v51, vcc
	v_subrev_u32_e32 v51, 28, v90
	v_cmp_lt_i32_e32 vcc, v51, v86
	v_add_f32_e32 v37, 1.0, v35
	v_rcp_f32_e32 v37, v37
	s_or_b64 vcc, s[8:9], vcc
	v_subrev_u32_e32 v51, 55, v90
	v_mul_f32_e32 v35, v35, v37
	v_cndmask_b32_e32 v111, 0, v35, vcc
	v_min_f32_e32 v35, 0x42700000, v54
	v_exp_f32_e32 v35, v35
	v_cndmask_b32_e32 v110, 1.0, v37, vcc
	v_cmp_lt_i32_e32 vcc, v51, v86
	s_or_b64 vcc, s[8:9], vcc
	v_add_f32_e32 v37, 1.0, v35
	v_rcp_f32_e32 v37, v37
	s_nop 0
	v_mul_f32_e32 v35, v35, v37
	v_cndmask_b32_e32 v54, 0, v35, vcc
	v_min_f32_e32 v35, 0x42700000, v38
	v_exp_f32_e32 v35, v35
	v_cndmask_b32_e32 v51, 1.0, v37, vcc
	v_subrev_u32_e32 v38, 23, v90
	v_cmp_lt_i32_e32 vcc, v38, v86
	v_add_f32_e32 v37, 1.0, v35
	v_rcp_f32_e32 v37, v37
	s_or_b64 vcc, s[8:9], vcc
	v_subrev_u32_e32 v38, 54, v90
	v_mul_f32_e32 v35, v35, v37
	v_cndmask_b32_e32 v112, 0, v35, vcc
	v_min_f32_e32 v35, 0x42700000, v55
	v_exp_f32_e32 v35, v35
	v_cndmask_b32_e32 v53, 1.0, v37, vcc
	v_cmp_lt_i32_e32 vcc, v38, v86
	s_or_b64 vcc, s[8:9], vcc
	v_add_f32_e32 v37, 1.0, v35
	v_rcp_f32_e32 v37, v37
	v_subrev_u32_e32 v38, 22, v90
	v_mul_f32_e32 v35, v35, v37
	v_cndmask_b32_e32 v113, 0, v35, vcc
	v_min_f32_e32 v35, 0x42700000, v39
	v_exp_f32_e32 v35, v35
	v_cndmask_b32_e32 v55, 1.0, v37, vcc
	v_cmp_lt_i32_e32 vcc, v38, v86
	s_or_b64 vcc, s[8:9], vcc
	v_add_f32_e32 v37, 1.0, v35
	v_rcp_f32_e32 v37, v37
	v_subrev_u32_e32 v38, 53, v90
	v_mul_f32_e32 v35, v35, v37
	v_cndmask_b32_e32 v115, 0, v35, vcc
	v_min_f32_e32 v35, 0x42700000, v56
	v_exp_f32_e32 v35, v35
	v_cndmask_b32_e32 v114, 1.0, v37, vcc
	v_cmp_lt_i32_e32 vcc, v38, v86
	s_or_b64 vcc, s[8:9], vcc
	v_add_f32_e32 v37, 1.0, v35
	v_rcp_f32_e32 v37, v37
	v_subrev_u32_e32 v38, 21, v90
	v_mul_f32_e32 v35, v35, v37
	v_cndmask_b32_e32 v117, 0, v35, vcc
	v_min_f32_e32 v35, 0x42700000, v40
	v_exp_f32_e32 v35, v35
	v_cndmask_b32_e32 v116, 1.0, v37, vcc
	v_cmp_lt_i32_e32 vcc, v38, v86
	s_or_b64 vcc, s[8:9], vcc
	v_add_f32_e32 v37, 1.0, v35
	v_rcp_f32_e32 v37, v37
	v_subrev_u32_e32 v38, 52, v90
	v_mul_f32_e32 v35, v35, v37
	v_cndmask_b32_e32 v119, 0, v35, vcc
	v_min_f32_e32 v35, 0x42700000, v57
	v_exp_f32_e32 v35, v35
	v_cndmask_b32_e32 v118, 1.0, v37, vcc
	v_cmp_lt_i32_e32 vcc, v38, v86
	s_or_b64 vcc, s[8:9], vcc
	v_add_f32_e32 v37, 1.0, v35
	v_rcp_f32_e32 v37, v37
	v_subrev_u32_e32 v38, 20, v90
	v_mul_f32_e32 v35, v35, v37
	v_cndmask_b32_e32 v121, 0, v35, vcc
	v_min_f32_e32 v35, 0x42700000, v41
	v_exp_f32_e32 v35, v35
	v_cndmask_b32_e32 v120, 1.0, v37, vcc
	v_cmp_lt_i32_e32 vcc, v38, v86
	s_or_b64 vcc, s[8:9], vcc
	v_add_f32_e32 v37, 1.0, v35
	v_rcp_f32_e32 v37, v37
	v_subrev_u32_e32 v38, 47, v90
	v_subrev_u32_e32 v41, 45, v90
	v_mul_f32_e32 v35, v35, v37
	v_cndmask_b32_e32 v123, 0, v35, vcc
	v_min_f32_e32 v35, 0x42700000, v58
	v_exp_f32_e32 v35, v35
	v_cndmask_b32_e32 v122, 1.0, v37, vcc
	v_cmp_lt_i32_e32 vcc, v38, v86
	s_or_b64 vcc, s[8:9], vcc
	v_add_f32_e32 v37, 1.0, v35
	v_rcp_f32_e32 v37, v37
	v_add_u32_e32 v38, -15, v90
	v_mul_f32_e32 v35, v35, v37
	v_cndmask_b32_e32 v124, 0, v35, vcc
	v_min_f32_e32 v35, 0x42700000, v42
	v_exp_f32_e32 v35, v35
	v_cndmask_b32_e32 v39, 1.0, v37, vcc
	v_cmp_lt_i32_e32 vcc, v38, v86
	s_or_b64 vcc, s[8:9], vcc
	v_add_f32_e32 v37, 1.0, v35
	v_rcp_f32_e32 v37, v37
	v_subrev_u32_e32 v38, 46, v90
	v_mul_f32_e32 v35, v35, v37
	v_cndmask_b32_e32 v125, 0, v35, vcc
	v_min_f32_e32 v35, 0x42700000, v59
	v_exp_f32_e32 v35, v35
	v_cndmask_b32_e32 v40, 1.0, v37, vcc
; DI float fast_exp2(float x) { return __builtin_amdgcn_exp2f(x); }
; DI float fast_rcp(float x) { return __builtin_amdgcn_rcpf(x); }
; DI float xhalf_other(float v) { const unsigned b = __float_as_uint(v); auto rr = __builtin_amdgcn_permlane32_swap(b, b, false, false); return __uint_as_float(rr[0] ^ rr[1] ^ b); }
; DI void sb_wg_unit(bf16_t* act, int b, int hh, int Qb, LAS unsigned char* lds, volatile LAS unsigned* ctl, int tid, int wid, int lane) {
;     ...
;             for (int i = 0; i < 16; ++i) {
;                 const int kl = (i & 3) + 8 * (i >> 2) + 4 * h;
;                 { const float e = fast_exp2(fminf(p0[i], 60.f)); const float f = fast_rcp(1.f + e);
;                   const bool valid = !diag || (kv0 + kl < qpos); F0[i] = valid ? f : 1.f; p0[i] = valid ? e * f : 0.f; }
;                 { const float e = fast_exp2(fminf(p1[i], 60.f)); const float f = fast_rcp(1.f + e);
;                   const bool valid = !diag || (kv0 + 32 + kl < qpos); F1[i] = valid ? f : 1.f; p1[i] = valid ? e * f : 0.f; }
;             }
;             float G[8], Go[8];
; #pragma unroll
;             for (int g = 0; g < 4; ++g) { G[g] = (F0[4 * g] * F0[4 * g + 1]) * (F0[4 * g + 2] * F0[4 * g + 3]); G[4 + g] = (F1[4 * g] * F1[4 * g + 1]) * (F1[4 * g + 2] * F1[4 * g + 3]); }
; #pragma unroll
;             for (int g = 0; g < 8; ++g) Go[g] = xhalf_other(G[g]);
;             float run = C; float A[8];
; #pragma unroll
;             for (int g = 7; g >= 0; --g) { A[g] = run * (h == 0 ? Go[g] : 1.f); run *= (G[g] * Go[g]); }
	v_cmp_lt_i32_e32 vcc, v38, v86
	s_or_b64 vcc, s[8:9], vcc
	v_add_f32_e32 v37, 1.0, v35
	v_rcp_f32_e32 v37, v37
	v_add_u32_e32 v38, -14, v90
	v_mul_f32_e32 v35, v35, v37
	v_cndmask_b32_e32 v127, 0, v35, vcc
	v_min_f32_e32 v35, 0x42700000, v43
	v_exp_f32_e32 v35, v35
	v_cndmask_b32_e32 v126, 1.0, v37, vcc
	v_cmp_lt_i32_e32 vcc, v38, v86
	s_or_b64 vcc, s[8:9], vcc
	v_add_f32_e32 v37, 1.0, v35
	v_rcp_f32_e32 v37, v37
	v_subrev_u32_e32 v43, 38, v90
	v_mul_f32_e32 v35, v35, v37
	v_cndmask_b32_e32 v128, 0, v35, vcc
	v_min_f32_e32 v35, 0x42700000, v60
	v_exp_f32_e32 v35, v35
	v_cndmask_b32_e32 v38, 1.0, v37, vcc
	v_cmp_lt_i32_e32 vcc, v41, v86
	s_or_b64 vcc, s[8:9], vcc
	v_add_f32_e32 v37, 1.0, v35
	v_rcp_f32_e32 v37, v37
	v_add_u32_e32 v41, -13, v90
	v_mul_f32_e32 v35, v35, v37
	v_cndmask_b32_e32 v130, 0, v35, vcc
	v_min_f32_e32 v35, 0x42700000, v44
	v_exp_f32_e32 v35, v35
	v_cndmask_b32_e32 v129, 1.0, v37, vcc
	v_cmp_lt_i32_e32 vcc, v41, v86
	s_or_b64 vcc, s[8:9], vcc
	v_add_f32_e32 v37, 1.0, v35
	v_rcp_f32_e32 v37, v37
	v_subrev_u32_e32 v41, 44, v90
	v_mul_f32_e32 v35, v35, v37
	v_cndmask_b32_e32 v132, 0, v35, vcc
	v_min_f32_e32 v35, 0x42700000, v61
	v_exp_f32_e32 v35, v35
	v_cndmask_b32_e32 v131, 1.0, v37, vcc
	v_cmp_lt_i32_e32 vcc, v41, v86
	s_or_b64 vcc, s[8:9], vcc
	v_add_f32_e32 v37, 1.0, v35
	v_rcp_f32_e32 v37, v37
	v_add_u32_e32 v41, -12, v90
	v_mul_f32_e32 v35, v35, v37
	v_cndmask_b32_e32 v134, 0, v35, vcc
	v_min_f32_e32 v35, 0x42700000, v45
	v_exp_f32_e32 v35, v35
	v_cndmask_b32_e32 v133, 1.0, v37, vcc
	v_cmp_lt_i32_e32 vcc, v41, v86
	s_or_b64 vcc, s[8:9], vcc
	v_add_f32_e32 v37, 1.0, v35
	v_rcp_f32_e32 v37, v37
	v_subrev_u32_e32 v41, 39, v90
	v_mul_f32_e32 v35, v35, v37
	v_cndmask_b32_e32 v136, 0, v35, vcc
	v_min_f32_e32 v35, 0x42700000, v62
	v_exp_f32_e32 v35, v35
	v_cndmask_b32_e32 v135, 1.0, v37, vcc
	v_cmp_lt_i32_e32 vcc, v41, v86
	s_or_b64 vcc, s[8:9], vcc
	v_add_f32_e32 v37, 1.0, v35
	v_rcp_f32_e32 v37, v37
	v_add_u32_e32 v41, -7, v90
	v_mul_f32_e32 v44, v131, v135
	v_mul_f32_e32 v35, v35, v37
	v_cndmask_b32_e32 v137, 0, v35, vcc
	v_min_f32_e32 v35, 0x42700000, v46
	v_exp_f32_e32 v35, v35
	v_cndmask_b32_e32 v42, 1.0, v37, vcc
	v_cmp_lt_i32_e32 vcc, v41, v86
	s_or_b64 vcc, s[8:9], vcc
	v_add_f32_e32 v37, 1.0, v35
	v_rcp_f32_e32 v37, v37
	s_nop 0
	v_mul_f32_e32 v35, v35, v37
	v_cndmask_b32_e32 v138, 0, v35, vcc
	v_min_f32_e32 v35, 0x42700000, v63
	v_exp_f32_e32 v35, v35
	v_cndmask_b32_e32 v41, 1.0, v37, vcc
	v_cmp_lt_i32_e32 vcc, v43, v86
	s_or_b64 vcc, s[8:9], vcc
	v_add_f32_e32 v37, 1.0, v35
	v_rcp_f32_e32 v37, v37
	v_add_u32_e32 v43, -6, v90
	v_mul_f32_e32 v35, v35, v37
	v_cndmask_b32_e32 v139, 0, v35, vcc
	v_min_f32_e32 v35, 0x42700000, v47
	v_exp_f32_e32 v35, v35
	v_cndmask_b32_e32 v56, 1.0, v37, vcc
	v_cmp_lt_i32_e32 vcc, v43, v86
	s_or_b64 vcc, s[8:9], vcc
	v_add_f32_e32 v37, 1.0, v35
	v_rcp_f32_e32 v37, v37
	v_subrev_u32_e32 v43, 37, v90
	v_mul_f32_e32 v35, v35, v37
	v_cndmask_b32_e32 v141, 0, v35, vcc
	v_min_f32_e32 v35, 0x42700000, v64
	v_exp_f32_e32 v35, v35
	v_cndmask_b32_e32 v140, 1.0, v37, vcc
	v_cmp_lt_i32_e32 vcc, v43, v86
	s_or_b64 vcc, s[8:9], vcc
	v_add_f32_e32 v37, 1.0, v35
	v_rcp_f32_e32 v37, v37
	v_add_u32_e32 v43, -5, v90
	v_mul_f32_e32 v41, v41, v140
	v_mul_f32_e32 v35, v35, v37
	v_cndmask_b32_e32 v63, 0, v35, vcc
	v_min_f32_e32 v35, 0x42700000, v48
	v_exp_f32_e32 v35, v35
	v_cndmask_b32_e32 v58, 1.0, v37, vcc
	v_cmp_lt_i32_e32 vcc, v43, v86
	s_or_b64 vcc, s[8:9], vcc
	v_add_f32_e32 v37, 1.0, v35
	v_rcp_f32_e32 v37, v37
	v_subrev_u32_e32 v43, 36, v90
	v_mul_f32_e32 v35, v35, v37
	v_cndmask_b32_e32 v143, 0, v35, vcc
	v_min_f32_e32 v35, 0x42700000, v65
	v_exp_f32_e32 v35, v35
	v_cndmask_b32_e32 v142, 1.0, v37, vcc
	v_cmp_lt_i32_e32 vcc, v43, v86
	s_or_b64 vcc, s[8:9], vcc
	v_add_f32_e32 v37, 1.0, v35
	v_rcp_f32_e32 v37, v37
	v_add_u32_e32 v43, -4, v90
	v_mul_f32_e32 v35, v35, v37
	v_cndmask_b32_e32 v62, 0, v35, vcc
	v_min_f32_e32 v35, 0x42700000, v49
	v_exp_f32_e32 v35, v35
	v_cndmask_b32_e32 v60, 1.0, v37, vcc
	v_cmp_lt_i32_e32 vcc, v43, v86
	s_or_b64 vcc, s[8:9], vcc
	v_add_f32_e32 v37, 1.0, v35
	v_rcp_f32_e32 v37, v37
	s_mov_b32 s8, 0x800000
	v_mul_f32_e32 v35, v35, v37
	v_cndmask_b32_e32 v144, 1.0, v37, vcc
	v_cndmask_b32_e32 v145, 0, v35, vcc
	v_mul_f32_e32 v35, v101, v103
	v_mul_f32_e32 v37, v107, v110
	v_mul_f32_e32 v43, v35, v37
	v_mul_f32_e32 v35, v51, v55
	v_mul_f32_e32 v37, v116, v120
	v_mul_f32_e32 v51, v35, v37
	v_mul_f32_e32 v35, v53, v114
	v_mul_f32_e32 v37, v118, v122
	v_mul_f32_e32 v37, v35, v37
	v_mul_f32_e32 v35, v39, v126
	v_mul_f32_e32 v39, v129, v133
	v_mul_f32_e32 v46, v35, v39
	v_mov_b32_e32 v35, v51
	v_mov_b32_e32 v45, v51
	s_nop 1
	v_permlane32_swap_b32_e32 v35, v45
	v_xor_b32_e32 v35, v35, v45
	v_mov_b32_e32 v45, v46
	v_mov_b32_e32 v47, v46
	s_nop 1
	v_permlane32_swap_b32_e32 v45, v47
	v_xor_b32_e32 v45, v45, v47
	v_xor_b32_e32 v47, v45, v46
	v_mov_b32_e32 v45, v43
	v_mov_b32_e32 v48, v43
	s_nop 1
	v_permlane32_swap_b32_e32 v45, v48
	v_xor_b32_e32 v45, v45, v48
	v_xor_b32_e32 v57, v45, v43
	v_mov_b32_e32 v45, v37
	v_mov_b32_e32 v48, v37
	v_mul_f32_e32 v39, v142, v144
	s_nop 0
	v_permlane32_swap_b32_e32 v45, v48
	v_xor_b32_e32 v45, v45, v48
	v_pk_mul_f32 v[40:41], v[40:41], v[38:39]
	v_xor_b32_e32 v48, v45, v37
	v_mov_b32_e32 v39, v41
	v_mov_b32_e32 v45, v41
	s_nop 1
	v_permlane32_swap_b32_e32 v39, v45
	v_xor_b32_e32 v39, v39, v45
	v_xor_b32_e32 v45, v39, v41
	v_pk_mul_f32 v[40:41], v[40:41], v[44:45]
	v_mul_f32_e32 v59, v37, v48
	v_mov_b32_e32 v39, v40
	v_mov_b32_e32 v44, v40
	s_nop 1
; #define LAS __attribute__((address_space(3)))
; #define MFMA32(a, b, c) __builtin_amdgcn_mfma_f32_32x32x16_bf16((a), (b), (c), 0, 0, 0)
; DI s16x4 vtr(LAS const unsigned char* p) { return __builtin_bit_cast(s16x4, __builtin_amdgcn_ds_read_tr16_b64_v4i16((LAS v4i16_t*)p)); }
; DI void pv_tile(f32x16& o0, f32x16& o1, LAS const unsigned char* Vs, const f32x16& p0, const f32x16& p1, int lane) {
;     const int h = lane >> 5;
;     LAS const unsigned char* vb = Vs + (4 * h + ((lane & 15) >> 2)) * 64 + ((lane >> 4) & 1) * 32 + (lane & 3) * 8;
; #pragma unroll
;     for (int kh = 0; kh < 2; ++kh)
; #pragma unroll
;         for (int s2 = 0; s2 < 2; ++s2) {
;             const bf16x8 pb = kh ? pack8(p1, s2) : pack8(p0, s2);
;             const int ro = (32 * kh + 16 * s2) * 64;
;             const s16x4 l0 = vtr(vb + ro), h0 = vtr(vb + ro + 512), l1 = vtr(vb + 4096 + ro), h1 = vtr(vb + 4096 + ro + 512);
;             const bf16x8 v0 = (bf16x8){l0[0], l0[1], l0[2], l0[3], h0[0], h0[1], h0[2], h0[3]};
;             const bf16x8 v1 = (bf16x8){l1[0], l1[1], l1[2], l1[3], h1[0], h1[1], h1[2], h1[3]};
;             o0 = MFMA32(v0, pb, o0); o1 = MFMA32(v1, pb, o1);
;         }
; DI void sb_wg_unit(bf16_t* act, int b, int hh, int Qb, LAS unsigned char* lds, volatile LAS unsigned* ctl, int tid, int wid, int lane) {
;     ...
;             for (int g = 7; g >= 0; --g) { A[g] = run * (h == 0 ? Go[g] : 1.f); run *= (G[g] * Go[g]); }
; #pragma unroll
;             for (int g = 0; g < 4; ++g) {
;                 { float bt = A[g]; p0[4 * g + 3] *= bt; bt *= F0[4 * g + 3]; p0[4 * g + 2] *= bt; bt *= F0[4 * g + 2]; p0[4 * g + 1] *= bt; bt *= F0[4 * g + 1]; p0[4 * g] *= bt; }
;                 { float bt = A[4 + g]; p1[4 * g + 3] *= bt; bt *= F1[4 * g + 3]; p1[4 * g + 2] *= bt; bt *= F1[4 * g + 2]; p1[4 * g + 1] *= bt; bt *= F1[4 * g + 1]; p1[4 * g] *= bt; }
;             }
;             C = run;
;             pv_tile(o0, o1, Vs, p0, p1, lane);
;             if (__all(C < 1.17549435e-38f)) done = true;
;             --t;
	v_permlane32_swap_b32_e32 v39, v44
	v_xor_b32_e32 v39, v39, v44
	v_xor_b32_e32 v90, v39, v40
	v_cndmask_b32_e64 v39, 1.0, v45, s[42:43]
	v_mul_f32_e32 v101, v91, v39
	v_cndmask_b32_e64 v39, 1.0, v90, s[42:43]
	v_pk_mul_f32 v[40:41], v[40:41], v[90:91]
	v_pk_mul_f32 v[42:43], v[42:43], v[56:57]
	v_mul_f32_e32 v49, v39, v41
	v_pk_mul_f32 v[40:41], v[40:41], v[40:41] op_sel:[0,1] op_sel_hi:[1,0]
	v_cndmask_b32_e64 v39, 1.0, v48, s[42:43]
	v_mov_b32_e32 v61, v40
	v_mul_f32_e32 v45, v39, v40
	v_pk_mul_f32 v[40:41], v[58:59], v[60:61]
	v_cndmask_b32_e64 v37, 1.0, v57, s[42:43]
	v_pk_mul_f32 v[42:43], v[42:43], v[40:41]
	v_mul_f32_e32 v48, v37, v41
	v_mov_b32_e32 v39, v42
	v_mov_b32_e32 v40, v42
	s_nop 1
	v_permlane32_swap_b32_e32 v39, v40
	v_xor_b32_e32 v39, v39, v40
	v_xor_b32_e32 v39, v39, v42
	v_cndmask_b32_e64 v37, 1.0, v39, s[42:43]
	v_mul_f32_e32 v64, v37, v43
	v_mul_f32_e32 v37, v42, v39
	v_xor_b32_e32 v35, v35, v51
	v_mul_f32_e32 v37, v37, v43
	v_mul_f32_e32 v53, v46, v47
	v_pk_mul_f32 v[40:41], v[52:53], v[36:37]
	v_pk_mul_f32 v[42:43], v[50:51], v[34:35]
	v_cndmask_b32_e64 v39, 1.0, v47, s[42:43]
	v_pk_mul_f32 v[42:43], v[42:43], v[40:41]
	v_mul_f32_e32 v57, v39, v37
	v_cndmask_b32_e64 v39, 1.0, v35, s[42:43]
	v_mov_b32_e32 v35, v42
	v_mov_b32_e32 v37, v42
	s_nop 1
	v_permlane32_swap_b32_e32 v35, v37
	v_xor_b32_e32 v35, v35, v37
	v_xor_b32_e32 v35, v35, v42
	v_mul_f32_e32 v39, v39, v41
	v_cndmask_b32_e64 v37, 1.0, v35, s[42:43]
	v_mul_f32_e32 v37, v37, v43
	v_mul_f32_e32 v35, v42, v35
	v_mul_f32_e32 v50, v121, v39
	v_mul_f32_e32 v39, v120, v39
	v_mul_f32_e32 v91, v35, v43
	v_mul_f32_e32 v35, v36, v37
	v_mul_f32_e32 v51, v117, v39
	v_mul_f32_e32 v39, v116, v39
	v_mul_f32_e32 v42, v105, v35
	v_mul_f32_e32 v35, v52, v35
	v_mul_f32_e32 v52, v113, v39
	v_mul_f32_e32 v39, v55, v39
	v_mul_f32_e32 v43, v122, v45
	v_mul_f32_e32 v55, v54, v39
	v_mul_f32_e32 v39, v123, v45
	v_mul_f32_e32 v45, v118, v43
	v_mul_f32_e32 v41, v119, v43
	v_mul_f32_e32 v43, v115, v45
	v_mul_f32_e32 v45, v114, v45
	v_mul_f32_e32 v46, v112, v45
	v_mul_f32_e32 v45, v133, v57
	v_mul_f32_e32 v54, v134, v57
	v_mul_f32_e32 v57, v130, v45
	v_mul_f32_e32 v45, v129, v45
	v_mul_f32_e32 v59, v127, v45
	v_mul_f32_e32 v45, v126, v45
	v_mul_f32_e32 v34, v34, v35
	v_mul_f32_e32 v36, v110, v48
	v_mul_f32_e32 v61, v124, v45
	v_mul_f32_e32 v45, v136, v49
	v_mul_f32_e32 v49, v135, v49
	v_add_u32_e32 v90, s13, v87
	v_mul_f32_e32 v40, v109, v37
	v_mul_f32_e32 v44, v102, v35
	v_mul_f32_e32 v47, v98, v34
	v_mul_f32_e32 v34, v111, v48
	v_mul_f32_e32 v35, v108, v36
	v_mul_f32_e32 v53, v131, v49
	ds_read_b64_tr_b16 v[108:109], v90 offset:8192
	ds_read_b64_tr_b16 v[110:111], v90 offset:8704
	ds_read_b64_tr_b16 v[112:113], v90 offset:12288
	ds_read_b64_tr_b16 v[114:115], v90 offset:12800
	v_mul_f32_e32 v48, v132, v49
	v_mul_f32_e32 v49, v128, v53
	v_mul_f32_e32 v38, v38, v53
	v_mul_f32_e32 v53, v60, v64
	v_mul_f32_e32 v37, v107, v36
	v_mul_f32_e32 v63, v63, v53
	v_mul_f32_e32 v53, v58, v53
	v_mul_f32_e32 v36, v104, v37
	v_mul_f32_e32 v37, v103, v37
	v_mul_f32_e32 v62, v62, v64
	v_mul_f32_e32 v64, v139, v53
	v_mul_f32_e32 v53, v56, v53
	v_mul_f32_e32 v37, v100, v37
	v_mul_f32_e32 v65, v137, v53
	v_mul_f32_e32 v53, v145, v101
	v_mul_f32_e32 v58, v144, v101
	v_cvt_pk_bf16_f32 v100, v47, v44
	v_cvt_pk_bf16_f32 v101, v42, v40
	v_cvt_pk_bf16_f32 v102, v55, v52
	v_cvt_pk_bf16_f32 v103, v51, v50
	v_mul_f32_e32 v38, v125, v38
	v_mul_f32_e32 v60, v142, v58
	s_waitcnt lgkmcnt(2)
	v_mfma_f32_32x32x16_bf16 v[18:33], v[108:111], v[100:103], v[18:33]
	v_mul_f32_e32 v56, v143, v58
	v_mul_f32_e32 v58, v141, v60
	v_mul_f32_e32 v60, v140, v60
	v_mul_f32_e32 v60, v138, v60
	v_cmp_gt_f32_e32 vcc, s8, v91
	s_cmp_eq_u64 vcc, exec
	s_cselect_b64 s[8:9], -1, 0
	s_waitcnt lgkmcnt(0)
	v_mfma_f32_32x32x16_bf16 v[2:17], v[112:115], v[100:103], v[2:17]
	v_cvt_pk_bf16_f32 v102, v65, v64
	v_cvt_pk_bf16_f32 v103, v63, v62
	ds_read_b64_tr_b16 v[62:63], v90 offset:9216
	ds_read_b64_tr_b16 v[64:65], v90 offset:9728
	ds_read_b64_tr_b16 v[108:109], v90 offset:13312
	ds_read_b64_tr_b16 v[110:111], v90 offset:13824
	v_cvt_pk_bf16_f32 v100, v61, v59
	v_cvt_pk_bf16_f32 v101, v57, v54
	s_add_i32 s24, s24, -1
	s_cmp_le_i32 s10, s23
	s_waitcnt lgkmcnt(2)
	v_mfma_f32_32x32x16_bf16 v[18:33], v[62:65], v[100:103], v[18:33]
	v_cvt_pk_bf16_f32 v62, v37, v36
	v_cvt_pk_bf16_f32 v63, v35, v34
	v_cvt_pk_bf16_f32 v64, v46, v43
	v_cvt_pk_bf16_f32 v65, v41, v39
	ds_read_b64_tr_b16 v[34:35], v90 offset:10240
	ds_read_b64_tr_b16 v[36:37], v90 offset:10752
	ds_read_b64_tr_b16 v[40:41], v90 offset:14336
	ds_read_b64_tr_b16 v[42:43], v90 offset:14848
	s_cselect_b64 s[10:11], -1, 0
	s_or_b64 s[10:11], s[8:9], s[10:11]
	s_waitcnt lgkmcnt(4)
	v_mfma_f32_32x32x16_bf16 v[2:17], v[108:111], v[100:103], v[2:17]
	s_sub_i32 s12, s12, 64
	v_add_u32_e32 v87, 0x4000, v87
	s_andn2_b64 vcc, exec, s[10:11]
	s_waitcnt lgkmcnt(2)
	v_mfma_f32_32x32x16_bf16 v[18:33], v[34:37], v[62:65], v[18:33]
	v_cvt_pk_bf16_f32 v34, v38, v49
	v_cvt_pk_bf16_f32 v35, v48, v45
	v_cvt_pk_bf16_f32 v36, v60, v58
	v_cvt_pk_bf16_f32 v37, v56, v53
	s_waitcnt lgkmcnt(0)
	v_mfma_f32_32x32x16_bf16 v[2:17], v[40:43], v[62:65], v[2:17]
	ds_read_b64_tr_b16 v[38:39], v90 offset:11264
	ds_read_b64_tr_b16 v[40:41], v90 offset:11776
	ds_read_b64_tr_b16 v[42:43], v90 offset:15360
	ds_read_b64_tr_b16 v[44:45], v90 offset:15872
	s_waitcnt lgkmcnt(2)
	v_mfma_f32_32x32x16_bf16 v[18:33], v[38:41], v[34:37], v[18:33]
	s_waitcnt lgkmcnt(0)
	v_mfma_f32_32x32x16_bf16 v[2:17], v[42:45], v[34:37], v[2:17]
	s_cbranch_vccnz .LBB0_355
